# rope table block moved from the end of P0 to before the CTL-zero/XN part (registers renamed, SGPRs saved in VGPR lanes) so its f64 math overlaps the weight-copy traffic
# speedup vs baseline: 1.0109x; 1.0014x over previous
; __global__ void __launch_bounds__(NWAVES * 64, 2) fwd_kernel(Args args) {
;     ...
;         for (int i = vcu * 512 + tid; i < M * 8; i += G * 512) {
;             const int m = i >> 3, f = i & 7;
;             const float invf = (f == 0) ? 1.0f : (f == 1) ? 0.1939227432012558f : (f == 2) ? 0.03760603070259094f : (f == 3) ? 0.007292664609849453f : (f == 4) ? 0.0014142135623842478f
;                              : (f == 5) ? 0.00027424818836152554f : (f == 6) ? 5.318296098266728e-05f : 1.0313386155758053e-05f;
;             const float ang = (float)positions[m] * invf;
;             float sn, cs; sincos_d((double)ang, sn, cs);
;             ropec[i] = (f16_t)cs; ropes[i] = (f16_t)sn;
.LBB0_95:
	s_cmp_lg_u32 s27, 0
	s_cselect_b64 s[16:17], -1, 0
	s_lshl_b32 s5, s27, 1
	v_cmp_gt_i32_e32 vcc, s5, v130
	s_and_b64 s[18:19], s[16:17], vcc
	s_and_saveexec_b64 s[16:17], s[18:19]
	s_cbranch_execz .LBB0_82
	v_mov_b32_e32 v133, s27
	v_cmp_gt_i32_e32 vcc, s27, v130
	s_nop 1
	v_cndmask_b32_e64 v133, v133, 0, vcc
	v_sub_u32_e32 v130, v130, v133
	v_lshlrev_b32_e32 v133, 1, v130
	v_and_b32_e32 v133, 0xffffff00, v133
	v_cndmask_b32_e64 v137, v136, 0, vcc
	v_and_b32_e32 v130, 0x7f, v130
	v_or3_b32 v130, v130, v137, v133
	s_branch .LBB0_82
.Lrf_drain:
	s_waitcnt vmcnt(0)
.LBB0_97:
	v_lshl_or_b32 v66, s85, 9, v0
	v_writelane_b32 v204, s2, 0
	v_writelane_b32 v204, s3, 1
	v_writelane_b32 v204, s4, 2
	v_writelane_b32 v204, s5, 3
	v_writelane_b32 v204, s6, 4
	v_writelane_b32 v204, s7, 5
	v_writelane_b32 v204, s8, 6
	v_writelane_b32 v204, s9, 7
	v_writelane_b32 v204, s12, 8
	v_writelane_b32 v204, s13, 9
	v_writelane_b32 v204, s14, 10
	v_writelane_b32 v204, s15, 11
	v_writelane_b32 v204, s16, 12
	v_writelane_b32 v204, s17, 13
	v_writelane_b32 v204, s18, 14
	v_writelane_b32 v204, s19, 15
	v_writelane_b32 v204, s20, 16
	v_writelane_b32 v204, s21, 17
	v_writelane_b32 v204, s24, 18
	v_writelane_b32 v204, s25, 19
	v_writelane_b32 v204, s26, 20
	v_writelane_b32 v204, s27, 21
	v_writelane_b32 v204, s28, 22
	v_writelane_b32 v204, s29, 23
	v_writelane_b32 v204, s30, 24
	v_writelane_b32 v204, s36, 25
	v_writelane_b32 v204, s37, 26
	v_writelane_b32 v204, s46, 27
	v_writelane_b32 v204, s47, 28
	v_mov_b32_e32 v202, v66
	v_ashrrev_i32_e32 v203, 31, v202
	s_mov_b32 s2, 0x20000
	v_cmp_gt_i32_e32 vcc, s2, v202
	s_and_saveexec_b64 s[6:7], vcc
	s_cbranch_execz .Lrf_done
	v_and_b32_e32 v192, 7, v0
	s_lshl_b32 s8, s69, 9
	v_mov_b32_e32 v160, 0x372d07a8
	v_mov_b32_e32 v161, 0x385f10c5
	v_cmp_eq_u32_e32 vcc, 6, v192
	s_mov_b64 s[2:3], 0x1c00000
	s_ashr_i32 s9, s8, 31
	v_cndmask_b32_e32 v193, v160, v161, vcc
	v_lshl_add_u64 v[160:161], v[202:203], 1, s[22:23]
	s_mov_b32 s16, 0x6dc9c883
	s_mov_b32 s18, 0x54442d18
	s_mov_b32 s20, 0x33145c07
	s_mov_b32 s36, 0xe733b81f
	v_mov_b32_e32 v168, 0x1a01a01a
	v_mov_b32_e32 v172, 0x55555555
	v_lshl_add_u64 v[160:161], v[160:161], 0, s[2:3]
	s_lshl_b64 s[12:13], s[8:9], 1
	s_mov_b64 s[14:15], 0
	s_mov_b32 s17, 0x3fe45f30
	s_mov_b32 s19, 0xbff921fb
	s_mov_b32 s21, 0xbc91a626
	v_mov_b32_e32 v162, 0x13a86d09
	v_mov_b32_e32 v163, 0x3de61246
	s_mov_b32 s37, 0xbd6ae7f3
	v_mov_b32_e32 v164, 0x67f544e4
	v_mov_b32_e32 v165, 0xbe5ae645
	v_mov_b32_e32 v166, 0xa556c734
	v_mov_b32_e32 v167, 0x3ec71de3
	v_mov_b32_e32 v169, 0xbf2a01a0
	v_mov_b32_e32 v170, 0x11111111
	v_mov_b32_e32 v171, 0x3f811111
	v_mov_b32_e32 v173, 0xbfc55555
	v_mov_b32_e32 v174, 0xa8c07c9d
	v_mov_b32_e32 v175, 0xbda93974
	s_mov_b32 s47, 0x3d2ae7f3
	s_mov_b32 s46, s36
	v_mov_b32_e32 v176, 0xeff8d898
	v_mov_b32_e32 v177, 0x3e21eed8
	v_mov_b32_e32 v178, 0xb7789f5c
	v_mov_b32_e32 v179, 0xbe927e4f
	v_mov_b32_e32 v181, 0x3efa01a0
	v_mov_b32_e32 v180, v168
	v_mov_b32_e32 v182, 0x16c16c17
	v_mov_b32_e32 v183, 0xbf56c16c
	v_mov_b32_e32 v185, 0x3fa55555
	v_mov_b32_e32 v184, v172
	s_movk_i32 s9, 0x1ff
	s_movk_i32 s28, 0xffe
	s_movk_i32 s29, 0x40f
	s_mov_b32 s30, 0x8000
	v_mov_b32_e32 v194, 0x7c00
	v_mov_b32_e32 v195, 0x7e00
	s_branch .Lrf_140
.Lrf_138:
	s_andn2_saveexec_b64 s[4:5], s[4:5]
	s_or_b64 exec, exec, s[4:5]
	v_cndmask_b32_e64 v186, v188, v186, s[2:3]
	v_cndmask_b32_e64 v187, -v189, -v187, s[2:3]
	v_cndmask_b32_e32 v187, v187, v189, vcc
	v_cndmask_b32_e32 v186, v186, v188, vcc
	v_mov_b64_e32 v[188:189], v[190:191]
; __global__ void __launch_bounds__(NWAVES * 64, 2) fwd_kernel(Args args) {
;     ...
;         for (int i = vcu * 512 + tid; i < M * 8; i += G * 512) {
;             const int m = i >> 3, f = i & 7;
;             const float invf = (f == 0) ? 1.0f : (f == 1) ? 0.1939227432012558f : (f == 2) ? 0.03760603070259094f : (f == 3) ? 0.007292664609849453f : (f == 4) ? 0.0014142135623842478f
;                              : (f == 5) ? 0.00027424818836152554f : (f == 6) ? 5.318296098266728e-05f : 1.0313386155758053e-05f;
;             const float ang = (float)positions[m] * invf;
;             float sn, cs; sincos_d((double)ang, sn, cs);
;             ropec[i] = (f16_t)cs; ropes[i] = (f16_t)sn;
;         }
.Lrf_139:
	s_or_b64 exec, exec, s[24:25]
	v_and_or_b32 v188, v189, s9, v188
	v_cmp_ne_u32_e32 vcc, 0, v188
	v_lshrrev_b32_e32 v190, 8, v189
	v_bfe_u32 v191, v189, 20, 11
	v_cndmask_b32_e64 v188, 0, 1, vcc
	v_and_or_b32 v188, v190, s28, v188
	v_sub_u32_e32 v196, 0x3f1, v191
	v_or_b32_e32 v190, 0x1000, v188
	v_med3_i32 v196, v196, 0, 13
	v_lshrrev_b32_e32 v197, v196, v190
	v_lshlrev_b32_e32 v196, v196, v197
	v_cmp_ne_u32_e32 vcc, v196, v190
	v_add_u32_e32 v191, 0xfffffc10, v191
	v_lshl_or_b32 v196, v191, 12, v188
	v_cndmask_b32_e64 v190, 0, 1, vcc
	v_or_b32_e32 v190, v197, v190
	v_cmp_gt_i32_e32 vcc, 1, v191
	v_lshrrev_b32_e32 v189, 16, v189
	v_and_or_b32 v186, v187, s9, v186
	v_cndmask_b32_e32 v190, v196, v190, vcc
	v_and_b32_e32 v196, 7, v190
	v_cmp_lt_i32_e32 vcc, 5, v196
	v_lshrrev_b32_e32 v190, 2, v190
	v_add_u32_e32 v202, s8, v202
	v_cndmask_b32_e64 v197, 0, 1, vcc
	v_cmp_eq_u32_e32 vcc, 3, v196
	s_mov_b32 s2, 0x1ffff
	s_nop 0
	v_cndmask_b32_e64 v196, 0, 1, vcc
	v_or_b32_e32 v196, v196, v197
	v_add_u32_e32 v190, v190, v196
	v_cmp_gt_i32_e32 vcc, 31, v191
	s_nop 1
	v_cndmask_b32_e32 v190, v194, v190, vcc
	v_cmp_ne_u32_e32 vcc, 0, v188
	s_nop 1
	v_cndmask_b32_e32 v188, v194, v195, vcc
	v_cmp_eq_u32_e32 vcc, s29, v191
	s_nop 1
	v_cndmask_b32_e32 v188, v190, v188, vcc
	v_and_or_b32 v188, v189, s30, v188
	v_cmp_ne_u32_e32 vcc, 0, v186
	global_store_short v[160:161], v188, off
	v_lshrrev_b32_e32 v188, 8, v187
	v_cndmask_b32_e64 v186, 0, 1, vcc
	v_bfe_u32 v189, v187, 20, 11
	v_and_or_b32 v186, v188, s28, v186
	v_sub_u32_e32 v190, 0x3f1, v189
	v_or_b32_e32 v188, 0x1000, v186
	v_med3_i32 v190, v190, 0, 13
	v_lshrrev_b32_e32 v191, v190, v188
	v_lshlrev_b32_e32 v190, v190, v191
	v_cmp_ne_u32_e32 vcc, v190, v188
	v_add_u32_e32 v189, 0xfffffc10, v189
	v_lshl_or_b32 v190, v189, 12, v186
	v_cndmask_b32_e64 v188, 0, 1, vcc
	v_or_b32_e32 v188, v191, v188
	v_cmp_gt_i32_e32 vcc, 1, v189
	v_lshrrev_b32_e32 v187, 16, v187
	s_nop 0
	v_cndmask_b32_e32 v188, v190, v188, vcc
	v_and_b32_e32 v190, 7, v188
	v_cmp_lt_i32_e32 vcc, 5, v190
	v_lshrrev_b32_e32 v188, 2, v188
	s_nop 0
	v_cndmask_b32_e64 v191, 0, 1, vcc
	v_cmp_eq_u32_e32 vcc, 3, v190
	s_nop 1
	v_cndmask_b32_e64 v190, 0, 1, vcc
	v_or_b32_e32 v190, v190, v191
	v_add_u32_e32 v188, v188, v190
	v_cmp_gt_i32_e32 vcc, 31, v189
	s_nop 1
	v_cndmask_b32_e32 v188, v194, v188, vcc
	v_cmp_ne_u32_e32 vcc, 0, v186
	s_nop 1
	v_cndmask_b32_e32 v186, v194, v195, vcc
	v_cmp_eq_u32_e32 vcc, s29, v189
	s_nop 1
	v_cndmask_b32_e32 v186, v188, v186, vcc
	v_and_or_b32 v188, v187, s30, v186
	v_add_co_u32_e32 v186, vcc, 0x80000, v160
	s_nop 1
	v_addc_co_u32_e32 v187, vcc, 0, v161, vcc
	v_cmp_lt_i32_e32 vcc, s2, v202
	s_or_b64 s[14:15], vcc, s[14:15]
	v_lshl_add_u64 v[160:161], v[160:161], 0, s[12:13]
	global_store_short v[186:187], v188, off
	s_andn2_b64 exec, exec, s[14:15]
	s_cbranch_execz .Lrf_done
.Lrf_140:
	v_cmp_lt_i32_e32 vcc, 2, v192
	s_and_saveexec_b64 s[2:3], vcc
	s_xor_b64 s[2:3], exec, s[2:3]
	s_cbranch_execz .Lrf_152
	v_cmp_lt_i32_e32 vcc, 3, v192
	s_and_saveexec_b64 s[4:5], vcc
	s_xor_b64 s[4:5], exec, s[4:5]
	s_cbranch_execz .Lrf_149
	v_cmp_lt_i32_e32 vcc, 4, v192
	s_and_saveexec_b64 s[24:25], vcc
	s_xor_b64 s[24:25], exec, s[24:25]
	s_cbranch_execz .Lrf_146
	v_cmp_ne_u32_e32 vcc, 5, v192
	s_and_saveexec_b64 s[26:27], vcc
	s_xor_b64 s[26:27], exec, s[26:27]
	s_or_saveexec_b64 s[26:27], s[26:27]
	v_mov_b32_e32 v186, v193
	s_xor_b64 exec, exec, s[26:27]
	v_mov_b32_e32 v186, 0x398fc8f8
	s_or_b64 exec, exec, s[26:27]
.Lrf_146:
	s_andn2_saveexec_b64 s[24:25], s[24:25]
	v_mov_b32_e32 v186, 0x3ab95d22
	s_or_b64 exec, exec, s[24:25]
.Lrf_149:
	s_andn2_saveexec_b64 s[4:5], s[4:5]
	v_mov_b32_e32 v186, 0x3beef74e
	s_or_b64 exec, exec, s[4:5]
.Lrf_152:
	s_andn2_saveexec_b64 s[2:3], s[2:3]
	s_cbranch_execz .Lrf_158
	v_cmp_lt_i32_e32 vcc, 0, v192
	v_mov_b32_e32 v186, 1.0
	s_and_saveexec_b64 s[4:5], vcc
	s_cbranch_execz .Lrf_157
	v_cmp_lt_i32_e32 vcc, 1, v192
	s_and_saveexec_b64 s[24:25], vcc
	s_xor_b64 s[24:25], exec, s[24:25]
	s_or_saveexec_b64 s[24:25], s[24:25]
	v_mov_b32_e32 v186, 0x3d1a08c8
	s_xor_b64 exec, exec, s[24:25]
	v_mov_b32_e32 v186, 0x3e4693af
	s_or_b64 exec, exec, s[24:25]

; __device__ __forceinline__ void sincos_d(double a, float& sn, float& cs) {
;     const double q = __builtin_rint(a * 0.63661977236758134308);
;     double r = __builtin_fma(-q, 1.57079632679489655800e+00, a); r = __builtin_fma(-q, 6.12323399573676603587e-17, r);
;     const double r2 = r * r;
;     double s = -7.6471637318198164759e-13; s = s * r2 + 1.6059043836821614599e-10; s = s * r2 - 2.5052108385441718775e-08; s = s * r2 + 2.7557319223985890653e-06;
;     s = s * r2 - 1.9841269841269841270e-04; s = s * r2 + 8.3333333333333333333e-03; s = s * r2 - 1.6666666666666666667e-01; s = s * r2 * r + r;
;     double c = 4.7794773323873852974e-14; c = c * r2 - 1.1470745597729724714e-11; c = c * r2 + 2.0876756987868098979e-09; c = c * r2 - 2.7557319223985890653e-07;
;     c = c * r2 + 2.4801587301587301587e-05; c = c * r2 - 1.3888888888888888889e-03; c = c * r2 + 4.1666666666666666667e-02; c = c * r2 - 0.5; c = c * r2 + 1.0;
;     const int qi = (int)(long long)q & 3;
;     const double ss = (qi == 0) ? s : (qi == 1) ? c : (qi == 2) ? -s : -c;
;     const double cc = (qi == 0) ? c : (qi == 1) ? -s : (qi == 2) ? -c : s;
;     sn = (float)ss; cs = (float)cc;
; __global__ void __launch_bounds__(NWAVES * 64, 2) fwd_kernel(Args args) {
;     ...
;         for (int i = vcu * 512 + tid; i < (int)((CTL_RSS3 + 64 * 1024 - CTL_KMS) / 16); i += G * 512) *((u32x4*)(ws + WS_CTL + CTL_KMS) + i) = (u32x4){0u, 0u, 0u, 0u};
.Lrf_158:
	s_or_b64 exec, exec, s[2:3]
	v_ashrrev_i32_e32 v188, 3, v202
	v_ashrrev_i32_e32 v189, 31, v188
	v_lshl_add_u64 v[188:189], v[188:189], 2, s[40:41]
	v_mov_b32_e32 v187, v253
	s_movk_i32 s2, 0xffe0
	s_waitcnt vmcnt(0)
	v_cvt_f32_i32_e32 v187, v187
	v_mul_f32_e32 v186, v186, v187
	v_cvt_f64_f32_e32 v[186:187], v186
	v_mul_f64 v[188:189], v[186:187], s[16:17]
	v_rndne_f64_e32 v[188:189], v[188:189]
	v_fmac_f64_e32 v[186:187], s[18:19], v[188:189]
	v_ldexp_f64 v[190:191], v[188:189], s2
	v_fmac_f64_e32 v[186:187], s[20:21], v[188:189]
	v_floor_f64_e32 v[190:191], v[190:191]
	v_mul_f64 v[196:197], v[186:187], v[186:187]
	v_fmac_f64_e32 v[188:189], 0xc1f00000, v[190:191]
	v_fma_f64 v[190:191], s[36:37], v[196:197], v[162:163]
	v_fma_f64 v[198:199], s[46:47], v[196:197], v[174:175]
	v_cvt_u32_f64_e32 v200, v[188:189]
	v_fma_f64 v[188:189], v[196:197], v[190:191], v[164:165]
	v_fma_f64 v[198:199], v[196:197], v[198:199], v[176:177]
	v_fma_f64 v[188:189], v[196:197], v[188:189], v[166:167]
	v_fma_f64 v[198:199], v[196:197], v[198:199], v[178:179]
	v_fma_f64 v[188:189], v[196:197], v[188:189], v[168:169]
	v_fma_f64 v[198:199], v[196:197], v[198:199], v[180:181]
	v_fma_f64 v[188:189], v[196:197], v[188:189], v[170:171]
	v_fma_f64 v[198:199], v[196:197], v[198:199], v[182:183]
	v_fma_f64 v[188:189], v[196:197], v[188:189], v[172:173]
	v_fma_f64 v[198:199], v[196:197], v[198:199], v[184:185]
	v_and_b32_e32 v190, 3, v200
	v_mul_f64 v[188:189], v[196:197], v[188:189]
	v_fma_f64 v[198:199], v[196:197], v[198:199], -0.5
	v_fmac_f64_e32 v[186:187], v[186:187], v[188:189]
	v_fma_f64 v[188:189], v[196:197], v[198:199], 1.0
	v_cmp_lt_i32_e32 vcc, 0, v190
	s_and_saveexec_b64 s[24:25], vcc
	s_cbranch_execz .Lrf_139
	v_cmp_eq_u32_e32 vcc, 1, v190
	v_cmp_eq_u32_e64 s[2:3], 2, v190
	v_cmp_ne_u32_e64 s[4:5], 1, v190
	v_xor_b32_e32 v191, 0x80000000, v187
	v_mov_b32_e32 v190, v186
	s_and_saveexec_b64 s[26:27], s[4:5]
	s_xor_b64 s[4:5], exec, s[26:27]
	s_cbranch_execz .Lrf_138
	v_xor_b32_e32 v190, 0x80000000, v189
	v_cndmask_b32_e64 v191, v187, v190, s[2:3]
	v_cndmask_b32_e64 v190, v186, v188, s[2:3]
	s_branch .Lrf_138
.Lrf_done:
	s_or_b64 exec, exec, s[6:7]
	v_readlane_b32 s2, v204, 0
	v_readlane_b32 s3, v204, 1
	v_readlane_b32 s4, v204, 2
	v_readlane_b32 s5, v204, 3
	v_readlane_b32 s6, v204, 4
	v_readlane_b32 s7, v204, 5
	v_readlane_b32 s8, v204, 6
	v_readlane_b32 s9, v204, 7
	v_readlane_b32 s12, v204, 8
	v_readlane_b32 s13, v204, 9
	v_readlane_b32 s14, v204, 10
	v_readlane_b32 s15, v204, 11
	v_readlane_b32 s16, v204, 12
	v_readlane_b32 s17, v204, 13
	v_readlane_b32 s18, v204, 14
	v_readlane_b32 s19, v204, 15
	v_readlane_b32 s20, v204, 16
	v_readlane_b32 s21, v204, 17
	v_readlane_b32 s24, v204, 18
	v_readlane_b32 s25, v204, 19
	v_readlane_b32 s26, v204, 20
	v_readlane_b32 s27, v204, 21
	v_readlane_b32 s28, v204, 22
	v_readlane_b32 s29, v204, 23
	v_readlane_b32 s30, v204, 24
	v_readlane_b32 s36, v204, 25
	v_readlane_b32 s37, v204, 26
	v_readlane_b32 s46, v204, 27
	v_readlane_b32 s47, v204, 28
	s_nop 3
	s_movk_i32 s2, 0x6000
	v_cmp_gt_i32_e32 vcc, s2, v66
	v_ashrrev_i32_e32 v67, 31, v66
	s_and_saveexec_b64 s[2:3], vcc
	s_cbranch_execz .LBB0_100
	s_lshl_b32 s4, s69, 9
	v_lshl_add_u64 v[2:3], v[66:67], 4, s[22:23]
	s_mov_b64 s[8:9], 0x10000
	v_lshl_add_u64 v[6:7], v[2:3], 0, s[8:9]
	s_ashr_i32 s5, s4, 31
	v_mov_b32_e32 v2, 0
	s_lshl_b64 s[8:9], s[4:5], 4
	s_mov_b64 s[12:13], 0
	v_mov_b32_e32 v3, v2
	v_mov_b32_e32 v4, v2
	v_mov_b32_e32 v5, v2
	s_movk_i32 s5, 0x5fff
	v_mov_b32_e32 v8, v66

; __device__ __forceinline__ unsigned xb_ld(unsigned* p)              { return __hip_atomic_load(p, __ATOMIC_RELAXED, __HIP_MEMORY_SCOPE_AGENT); }
; __device__ __forceinline__ void xcd_barrier_complete(unsigned* bar, unsigned x, unsigned& nloc, unsigned& nx) {
;     const unsigned G = gridDim.x * gridDim.y * gridDim.z;
;     unsigned sum, cnt, mine, sp = 0u;
;     for (;;) {
;         sum = 0u; cnt = 0u; mine = 0u;
; #pragma unroll
;         for (unsigned j = 0; j < 16; ++j) { const unsigned c = xb_ld(&bar[XB_XCNT(j)]); sum += c; cnt += (c > 0u) ? 1u : 0u; mine = (j == x) ? c : mine; }
;         if (sum == G) break;
;         __builtin_amdgcn_s_sleep(1);
;         if ((++sp & 255u) == 0u) { if (xb_ld(&bar[XB_TMO])) break; if (sp > XB_SPIN_CAP) { atomicAdd(&bar[XB_TMO], 1u); break; } }
;     }
;     nloc = mine > 0u ? mine : 1u; nx = cnt > 0u ? cnt : 1u;
; }
; __device__ __forceinline__ void xcd_barrier(const XcdBarrier& b) {
;     asm volatile("s_waitcnt vmcnt(0)" ::: "memory");
;     __syncthreads();
;     if (threadIdx.x == 0) {
;         unsigned* bar = b.bar;
;         __builtin_amdgcn_s_waitcnt(0);
;         unsigned nloc = b.st[0], nx = b.st[1];
;         if (nloc == 0u) { xcd_barrier_complete(bar, b.x, nloc, nx); b.st[0] = nloc; b.st[1] = nx; }
.LBB0_136:
.LBB0_161:
.LBB0_162:
	s_cmp_gt_i32 s77, 1
	s_cselect_b64 s[36:37], -1, 0
	s_and_b64 s[0:1], s[0:1], s[36:37]
	s_andn2_b64 vcc, exec, s[0:1]
	s_cbranch_vccnz .LBB0_212
	s_waitcnt vmcnt(0)
	s_barrier
	s_and_saveexec_b64 s[2:3], s[92:93]
	s_cbranch_execz .LBB0_211
	v_mov_b32_e32 v2, s84
	s_waitcnt vmcnt(0) expcnt(0) lgkmcnt(0)
	ds_read_b32 v4, v2
	ds_read_b32 v2, v2 offset:4
	s_waitcnt lgkmcnt(1)
	v_cmp_ne_u32_e32 vcc, 0, v4
	s_cbranch_vccnz .LBB0_179
	v_readlane_b32 s4, v254, 0
	v_readlane_b32 s5, v254, 1
	s_load_dwordx2 s[8:9], s[4:5], 0x4
	s_add_u32 s4, s22, 0x4200
	s_addc_u32 s5, s23, 0
	s_add_u32 s6, s22, 0x4400
	s_addc_u32 s7, s23, 0
	s_waitcnt lgkmcnt(0)
	s_mul_i32 s28, s8, s69
	s_add_u32 s8, s22, 0x4500
	s_mul_i32 s28, s28, s9
	s_addc_u32 s9, s23, 0
	s_add_u32 s12, s22, 0x4600
	s_addc_u32 s13, s23, 0
	s_add_u32 s14, s22, 0x4700
	s_addc_u32 s15, s23, 0
	s_add_u32 s16, s22, 0x4800
	s_addc_u32 s17, s23, 0
	s_add_u32 s18, s22, 0x4900
	s_addc_u32 s19, s23, 0
	s_add_u32 s20, s22, 0x4a00
	s_addc_u32 s21, s23, 0
	s_add_u32 s24, s22, 0x4b00
	s_addc_u32 s25, s23, 0
	s_add_u32 s26, s22, 0x4c00
	s_addc_u32 s27, s23, 0
	s_add_u32 s40, s22, 0x4d00
	s_addc_u32 s41, s23, 0
	s_add_u32 s46, s22, 0x4e00
	s_addc_u32 s47, s23, 0
	s_add_u32 s52, s22, 0x4f00
	s_addc_u32 s53, s23, 0
	s_add_u32 s54, s22, 0x5000
	s_addc_u32 s55, s23, 0
	s_add_u32 s56, s22, 0x5100
	s_addc_u32 s57, s23, 0
	s_add_u32 s58, s22, 0x5200
	s_addc_u32 s59, s23, 0
	s_add_u32 s60, s22, 0x5300
	s_addc_u32 s61, s23, 0
	s_mov_b32 s29, 1
	v_mov_b32_e32 v18, 0
	s_branch .LBB0_167
